# XCD groups start the first GEMM phase at graded offsets (x * ~3 us): tile epilogues and seams of different XCDs no longer coincide
# speedup vs baseline: 1.0086x; 1.0086x over previous
; #define SEAM(k) do { if (IN(k) && IN((k) + 1)) xcd_barrier(xbar); } while (0)
; __global__ void __launch_bounds__(NTHREADS, 2) mega_fwd(Args a) {
;     ...
;     SEAM(0);
.LBB0_196:
	s_and_b32 s101, s2, 7
.Lstag_loop:
	s_cmp_eq_u32 s101, 0
	s_cbranch_scc1 .Lstag_done
	s_sleep 100
	s_sub_u32 s101, s101, 1
	s_branch .Lstag_loop
